# outproj value loop: four B-fragment reads hoisted above the DMA block, counted LDS waits
# baseline (speedup 1.0000x reference)
; DI void phase_outproj(const Params& P, char* shm) {
;     ...
;       for (int q = 0; q < 8; ++q) {
;         const bool more = (q < 6) || (x < 3);
;         if (q < 6) O_ISSUE(x, 18 + q, nxt);
;         else if (x < 3) O_ISSUE(x + 1, q - 6, nxt);
.LBB0_847:
	s_mul_i32 s98, s11, 0xc000
	v_or_b32_e32 v250, s98, v220
	v_add_u32_e32 v251, s98, v219
	ds_read_b128 v[234:237], v251 offset:2048
	ds_read_b128 v[238:241], v251 offset:4096
	ds_read_b128 v[242:245], v251 offset:6144
	ds_read_b128 v[246:249], v251 offset:8192
	s_cmp_lt_u32 s48, 6
	s_cselect_b64 s[20:21], -1, 0
	s_and_b64 vcc, exec, s[20:21]
	s_cbranch_vccnz .LBB0_849
	s_mov_b32 s53, 0x10000
	s_mov_b32 s52, 0x20000
	s_mov_b32 s49, 0x30000
	s_mov_b64 s[22:23], s[18:19]
	s_mov_b64 s[24:25], s[8:9]
	v_add_u32_e32 v222, 0xfffffe80, v128
	s_mov_b64 s[26:27], s[16:17]
	s_andn2_b64 vcc, exec, s[26:27]
	s_cbranch_vccz .LBB0_850
	s_branch .LBB0_851

.LBB0_851:
	s_or_b64 s[20:21], s[16:17], s[20:21]
	ds_read_b128 v[222:225], v250 offset:32768
	ds_read_b128 v[226:229], v250 offset:34816
	ds_read_b128 v[230:233], v251
	s_waitcnt lgkmcnt(0)
	v_mfma_f32_16x16x32_bf16 v[116:119], v[222:225], v[230:233], v[116:119]
	v_mfma_f32_16x16x32_bf16 v[108:111], v[226:229], v[230:233], v[108:111]
	ds_read_b128 v[230:233], v251 offset:10240
	v_mfma_f32_16x16x32_bf16 v[104:107], v[222:225], v[234:237], v[104:107]
	v_mfma_f32_16x16x32_bf16 v[96:99], v[226:229], v[234:237], v[96:99]
	ds_read_b128 v[234:237], v251 offset:12288
	v_mfma_f32_16x16x32_bf16 v[92:95], v[222:225], v[238:241], v[92:95]
	v_mfma_f32_16x16x32_bf16 v[84:87], v[226:229], v[238:241], v[84:87]
	ds_read_b128 v[238:241], v251 offset:14336
	v_mfma_f32_16x16x32_bf16 v[80:83], v[222:225], v[242:245], v[80:83]
	v_mfma_f32_16x16x32_bf16 v[72:75], v[226:229], v[242:245], v[72:75]
	v_mfma_f32_16x16x32_bf16 v[68:71], v[222:225], v[246:249], v[68:71]
	v_mfma_f32_16x16x32_bf16 v[60:63], v[226:229], v[246:249], v[60:63]
	s_waitcnt lgkmcnt(2)
	v_mfma_f32_16x16x32_bf16 v[52:55], v[222:225], v[230:233], v[52:55]
	v_mfma_f32_16x16x32_bf16 v[48:51], v[226:229], v[230:233], v[48:51]
	s_waitcnt lgkmcnt(1)
	v_mfma_f32_16x16x32_bf16 v[40:43], v[222:225], v[234:237], v[40:43]
	v_mfma_f32_16x16x32_bf16 v[36:39], v[226:229], v[234:237], v[36:39]
	s_waitcnt lgkmcnt(0)
	v_mfma_f32_16x16x32_bf16 v[28:31], v[222:225], v[238:241], v[28:31]
	v_mfma_f32_16x16x32_bf16 v[12:15], v[226:229], v[238:241], v[12:15]
	ds_read_b128 v[222:225], v250 offset:33792
	ds_read_b128 v[226:229], v250 offset:35840
	ds_read_b128 v[230:233], v251 offset:1024
	ds_read_b128 v[234:237], v251 offset:3072
	ds_read_b128 v[238:241], v251 offset:5120
	ds_read_b128 v[242:245], v251 offset:7168
	ds_read_b128 v[246:249], v251 offset:9216
	s_waitcnt lgkmcnt(4)
	v_mfma_f32_16x16x32_bf16 v[116:119], v[222:225], v[230:233], v[116:119]
	v_mfma_f32_16x16x32_bf16 v[108:111], v[226:229], v[230:233], v[108:111]
	ds_read_b128 v[230:233], v251 offset:11264
	s_waitcnt lgkmcnt(4)
	v_mfma_f32_16x16x32_bf16 v[104:107], v[222:225], v[234:237], v[104:107]
	v_mfma_f32_16x16x32_bf16 v[96:99], v[226:229], v[234:237], v[96:99]
	ds_read_b128 v[234:237], v251 offset:13312
	s_waitcnt lgkmcnt(4)
	v_mfma_f32_16x16x32_bf16 v[92:95], v[222:225], v[238:241], v[92:95]
	v_mfma_f32_16x16x32_bf16 v[84:87], v[226:229], v[238:241], v[84:87]
	ds_read_b128 v[238:241], v251 offset:15360
	s_waitcnt lgkmcnt(4)
	v_mfma_f32_16x16x32_bf16 v[80:83], v[222:225], v[242:245], v[80:83]
	v_mfma_f32_16x16x32_bf16 v[72:75], v[226:229], v[242:245], v[72:75]
	s_waitcnt lgkmcnt(3)
	v_mfma_f32_16x16x32_bf16 v[68:71], v[222:225], v[246:249], v[68:71]
	v_mfma_f32_16x16x32_bf16 v[60:63], v[226:229], v[246:249], v[60:63]
	s_waitcnt lgkmcnt(2)
	v_mfma_f32_16x16x32_bf16 v[52:55], v[222:225], v[230:233], v[52:55]
	v_mfma_f32_16x16x32_bf16 v[48:51], v[226:229], v[230:233], v[48:51]
	s_waitcnt lgkmcnt(1)
	v_mfma_f32_16x16x32_bf16 v[40:43], v[222:225], v[234:237], v[40:43]
	v_mfma_f32_16x16x32_bf16 v[36:39], v[226:229], v[234:237], v[36:39]
	s_waitcnt lgkmcnt(0)
	v_mfma_f32_16x16x32_bf16 v[28:31], v[222:225], v[238:241], v[28:31]
	v_mfma_f32_16x16x32_bf16 v[12:15], v[226:229], v[238:241], v[12:15]
	s_waitcnt lgkmcnt(0)
	s_andn2_b64 vcc, exec, s[20:21]
	s_mov_b64 s[20:21], -1
	s_cbranch_vccz .LBB0_853
	s_waitcnt vmcnt(0)
	s_mov_b64 s[20:21], 0
